# plus SwiGLU epilogue: paired stores merged into dwordx4 via permlane16 swap, global instead of flat stores
# speedup vs baseline: 1.0215x; 1.0096x over previous
.LBB0_29:
	s_or_b64 exec, exec, s[6:7]
	v_and_b32_e32 v142, 16, v225
	v_lshrrev_b32_e32 v143, 1, v142
	v_add_u32_e32 v142, v142, v143
	v_mov_b32_e32 v143, 0
	v_readlane_b32 s18, v255, 39
	v_readlane_b32 s19, v255, 40
	s_movk_i32 s11, 0x2c00
	s_waitcnt lgkmcnt(0)
	v_pk_mul_f32 v[124:125], v[124:125], v[164:165] op_sel_hi:[1,0]
	v_mov_b64_e32 v[130:131], s[18:19]
	v_mad_u64_u32 v[132:133], s[18:19], v168, s11, v[130:131]
	v_mov_b32_e32 v134, v133
	v_mad_u64_u32 v[134:135], s[18:19], v169, s11, v[134:135]
	v_mov_b32_e32 v133, v134
	v_mul_f32_e32 v134, 0xbfb8aa3b, v124
	v_mul_f32_e32 v135, 0xbfb8aa3b, v125
	v_exp_f32_e32 v134, v134
	v_exp_f32_e32 v135, v135
	v_pk_mul_f32 v[120:121], v[120:121], v[164:165] op_sel_hi:[1,0]
	s_lshl_b32 s6, s34, 7
	v_add_f32_e32 v134, 1.0, v134
	v_add_f32_e32 v135, 1.0, v135
	v_rcp_f32_e32 v134, v134
	v_rcp_f32_e32 v135, v135
	s_ashr_i32 s7, s6, 31
	s_lshl_b64 s[6:7], s[6:7], 1
	v_lshl_add_u64 v[132:133], v[132:133], 0, s[6:7]
	v_pk_mul_f32 v[124:125], v[124:125], v[134:135]
	v_pk_mul_f32 v[122:123], v[122:123], v[164:165] op_sel_hi:[1,0]
	v_pk_mul_f32 v[120:121], v[120:121], v[124:125]
	v_pk_mul_f32 v[124:125], v[126:127], v[164:165] op_sel_hi:[1,0]
	v_lshl_add_u64 v[132:133], v[132:133], 0, s[92:93]
	v_mul_f32_e32 v126, 0xbfb8aa3b, v124
	v_mul_f32_e32 v127, 0xbfb8aa3b, v125
	v_exp_f32_e32 v126, v126
	v_exp_f32_e32 v127, v127
	v_lshl_add_u64 v[132:133], v[132:133], 0, v[176:177]
	v_cvt_pk_bf16_f32 v120, v120, v121
	v_add_f32_e32 v126, 1.0, v126
	v_add_f32_e32 v127, 1.0, v127
	v_rcp_f32_e32 v126, v126
	v_rcp_f32_e32 v127, v127
	v_pk_mul_f32 v[116:117], v[116:117], v[164:165] op_sel_hi:[1,0]
	v_pk_mul_f32 v[112:113], v[112:113], v[164:165] op_sel_hi:[1,0]
	v_pk_mul_f32 v[114:115], v[114:115], v[164:165] op_sel_hi:[1,0]
	v_pk_mul_f32 v[124:125], v[124:125], v[126:127]
	v_pk_mul_f32 v[108:109], v[108:109], v[164:165] op_sel:[0,1]
	v_pk_mul_f32 v[122:123], v[122:123], v[124:125]
	v_pk_mul_f32 v[104:105], v[104:105], v[164:165] op_sel:[0,1]
	v_cvt_pk_bf16_f32 v121, v122, v123
	v_mov_b32_e32 v136, v120
	v_mov_b32_e32 v137, v121
	v_mul_f32_e32 v120, 0xbfb8aa3b, v116
	v_mul_f32_e32 v121, 0xbfb8aa3b, v117
	v_exp_f32_e32 v120, v120
	v_exp_f32_e32 v121, v121
	v_pk_mul_f32 v[106:107], v[106:107], v[164:165] op_sel:[0,1]
	v_pk_mul_f32 v[100:101], v[100:101], v[164:165] op_sel:[0,1]
	v_add_f32_e32 v120, 1.0, v120
	v_add_f32_e32 v121, 1.0, v121
	v_rcp_f32_e32 v120, v120
	v_rcp_f32_e32 v121, v121
	v_pk_mul_f32 v[96:97], v[96:97], v[164:165] op_sel:[0,1]
	v_pk_mul_f32 v[98:99], v[98:99], v[164:165] op_sel:[0,1]
	v_pk_mul_f32 v[92:93], v[92:93], v[160:161] op_sel_hi:[1,0]
	v_pk_mul_f32 v[116:117], v[116:117], v[120:121]
	v_pk_mul_f32 v[88:89], v[88:89], v[160:161] op_sel_hi:[1,0]
	v_pk_mul_f32 v[112:113], v[112:113], v[116:117]
	v_pk_mul_f32 v[116:117], v[118:119], v[164:165] op_sel_hi:[1,0]
	v_cvt_pk_bf16_f32 v112, v112, v113
	v_mul_f32_e32 v118, 0xbfb8aa3b, v116
	v_mul_f32_e32 v119, 0xbfb8aa3b, v117
	v_exp_f32_e32 v118, v118
	v_exp_f32_e32 v119, v119
	v_pk_mul_f32 v[90:91], v[90:91], v[160:161] op_sel_hi:[1,0]
	v_pk_mul_f32 v[84:85], v[84:85], v[160:161] op_sel_hi:[1,0]
	v_add_f32_e32 v118, 1.0, v118
	v_add_f32_e32 v119, 1.0, v119
	v_rcp_f32_e32 v118, v118
	v_rcp_f32_e32 v119, v119
	v_pk_mul_f32 v[80:81], v[80:81], v[160:161] op_sel_hi:[1,0]
	v_pk_mul_f32 v[82:83], v[82:83], v[160:161] op_sel_hi:[1,0]
	v_pk_mul_f32 v[76:77], v[76:77], v[160:161] op_sel:[0,1]
	v_pk_mul_f32 v[116:117], v[116:117], v[118:119]
	v_pk_mul_f32 v[72:73], v[72:73], v[160:161] op_sel:[0,1]
	v_pk_mul_f32 v[114:115], v[114:115], v[116:117]
	v_pk_mul_f32 v[74:75], v[74:75], v[160:161] op_sel:[0,1]
	v_cvt_pk_bf16_f32 v113, v114, v115
	v_mov_b32_e32 v138, v112
	v_mov_b32_e32 v139, v113
	v_lshl_add_u64 v[140:141], v[132:133], 0, v[142:143]
	s_nop 0
	v_permlane16_swap_b32_e32 v136, v138
	v_permlane16_swap_b32_e32 v137, v139
	global_store_dwordx4 v[140:141], v[136:139], off
	v_mad_u64_u32 v[112:113], s[18:19], v166, s11, v[130:131]
	v_mov_b32_e32 v114, v113
	v_mad_u64_u32 v[114:115], s[18:19], v167, s11, v[114:115]
	v_mov_b32_e32 v113, v114
	v_mul_f32_e32 v114, 0xbfb8aa3b, v108
	v_mul_f32_e32 v115, 0xbfb8aa3b, v109
	v_exp_f32_e32 v114, v114
	v_exp_f32_e32 v115, v115
	v_lshl_add_u64 v[112:113], v[112:113], 0, s[6:7]
	v_lshl_add_u64 v[112:113], v[112:113], 0, s[92:93]
	v_add_f32_e32 v114, 1.0, v114
	v_add_f32_e32 v115, 1.0, v115
	v_rcp_f32_e32 v114, v114
	v_rcp_f32_e32 v115, v115
	v_lshl_add_u64 v[112:113], v[112:113], 0, v[176:177]
	v_pk_mul_f32 v[68:69], v[68:69], v[160:161] op_sel:[0,1]
	v_pk_mul_f32 v[64:65], v[64:65], v[160:161] op_sel:[0,1]
	v_pk_mul_f32 v[108:109], v[108:109], v[114:115]
	v_pk_mul_f32 v[66:67], v[66:67], v[160:161] op_sel:[0,1]
	v_pk_mul_f32 v[104:105], v[104:105], v[108:109]
	v_pk_mul_f32 v[108:109], v[110:111], v[164:165] op_sel:[0,1]
	v_cvt_pk_bf16_f32 v104, v104, v105
	v_mul_f32_e32 v110, 0xbfb8aa3b, v108
	v_mul_f32_e32 v111, 0xbfb8aa3b, v109
	v_exp_f32_e32 v110, v110
	v_exp_f32_e32 v111, v111
	v_pk_mul_f32 v[60:61], v[60:61], v[156:157] op_sel_hi:[1,0]
	v_pk_mul_f32 v[56:57], v[56:57], v[156:157] op_sel_hi:[1,0]
	v_add_f32_e32 v110, 1.0, v110
	v_add_f32_e32 v111, 1.0, v111
	v_rcp_f32_e32 v110, v110
	v_rcp_f32_e32 v111, v111
	v_pk_mul_f32 v[58:59], v[58:59], v[156:157] op_sel_hi:[1,0]
	v_pk_mul_f32 v[52:53], v[52:53], v[156:157] op_sel_hi:[1,0]
	v_pk_mul_f32 v[48:49], v[48:49], v[156:157] op_sel_hi:[1,0]
	v_pk_mul_f32 v[108:109], v[108:109], v[110:111]
	v_pk_mul_f32 v[50:51], v[50:51], v[156:157] op_sel_hi:[1,0]
	v_pk_mul_f32 v[106:107], v[106:107], v[108:109]
	v_pk_mul_f32 v[44:45], v[44:45], v[156:157] op_sel:[0,1]
	v_cvt_pk_bf16_f32 v105, v106, v107
	v_mov_b32_e32 v136, v104
	v_mov_b32_e32 v137, v105
	v_mul_f32_e32 v104, 0xbfb8aa3b, v100
	v_mul_f32_e32 v105, 0xbfb8aa3b, v101
	v_exp_f32_e32 v104, v104
	v_exp_f32_e32 v105, v105
	v_pk_mul_f32 v[40:41], v[40:41], v[156:157] op_sel:[0,1]
	v_pk_mul_f32 v[42:43], v[42:43], v[156:157] op_sel:[0,1]
	v_add_f32_e32 v104, 1.0, v104
	v_add_f32_e32 v105, 1.0, v105
	v_rcp_f32_e32 v104, v104
	v_rcp_f32_e32 v105, v105
	v_pk_mul_f32 v[36:37], v[36:37], v[156:157] op_sel:[0,1]
	v_pk_mul_f32 v[32:33], v[32:33], v[156:157] op_sel:[0,1]
	v_pk_mul_f32 v[34:35], v[34:35], v[156:157] op_sel:[0,1]
	v_pk_mul_f32 v[100:101], v[100:101], v[104:105]
	v_pk_mul_f32 v[28:29], v[28:29], v[128:129] op_sel_hi:[1,0]
	v_pk_mul_f32 v[96:97], v[96:97], v[100:101]
	v_pk_mul_f32 v[100:101], v[102:103], v[164:165] op_sel:[0,1]
	v_cvt_pk_bf16_f32 v96, v96, v97
	v_mul_f32_e32 v102, 0xbfb8aa3b, v100
	v_mul_f32_e32 v103, 0xbfb8aa3b, v101
	v_exp_f32_e32 v102, v102
	v_exp_f32_e32 v103, v103
	v_pk_mul_f32 v[24:25], v[24:25], v[128:129] op_sel_hi:[1,0]
	v_pk_mul_f32 v[26:27], v[26:27], v[128:129] op_sel_hi:[1,0]
	v_add_f32_e32 v102, 1.0, v102
	v_add_f32_e32 v103, 1.0, v103
	v_rcp_f32_e32 v102, v102
	v_rcp_f32_e32 v103, v103
	v_pk_mul_f32 v[20:21], v[20:21], v[128:129] op_sel_hi:[1,0]
	v_pk_mul_f32 v[16:17], v[16:17], v[128:129] op_sel_hi:[1,0]
	v_pk_mul_f32 v[18:19], v[18:19], v[128:129] op_sel_hi:[1,0]
	v_pk_mul_f32 v[100:101], v[100:101], v[102:103]
	v_pk_mul_f32 v[12:13], v[12:13], v[128:129] op_sel:[0,1]
	v_pk_mul_f32 v[98:99], v[98:99], v[100:101]
	v_pk_mul_f32 v[8:9], v[8:9], v[128:129] op_sel:[0,1]
	v_cvt_pk_bf16_f32 v97, v98, v99
	v_mov_b32_e32 v138, v96
	v_mov_b32_e32 v139, v97
	v_lshl_add_u64 v[140:141], v[112:113], 0, v[142:143]
	s_nop 0
	v_permlane16_swap_b32_e32 v136, v138
	v_permlane16_swap_b32_e32 v137, v139
	global_store_dwordx4 v[140:141], v[136:139], off
	v_mad_u64_u32 v[96:97], s[18:19], v162, s11, v[130:131]
	v_mov_b32_e32 v98, v97
	v_mad_u64_u32 v[98:99], s[18:19], v163, s11, v[98:99]
	v_mov_b32_e32 v97, v98
	v_mul_f32_e32 v98, 0xbfb8aa3b, v92
	v_mul_f32_e32 v99, 0xbfb8aa3b, v93
	v_exp_f32_e32 v98, v98
	v_exp_f32_e32 v99, v99
	v_lshl_add_u64 v[96:97], v[96:97], 0, s[6:7]
	v_lshl_add_u64 v[96:97], v[96:97], 0, s[92:93]
	v_add_f32_e32 v98, 1.0, v98
	v_add_f32_e32 v99, 1.0, v99
	v_rcp_f32_e32 v98, v98
	v_rcp_f32_e32 v99, v99
	v_lshl_add_u64 v[96:97], v[96:97], 0, v[176:177]
	v_pk_mul_f32 v[10:11], v[10:11], v[128:129] op_sel:[0,1]
	v_pk_mul_f32 v[4:5], v[4:5], v[128:129] op_sel:[0,1]
	v_pk_mul_f32 v[92:93], v[92:93], v[98:99]
	v_pk_mul_f32 v[0:1], v[0:1], v[128:129] op_sel:[0,1]
	v_pk_mul_f32 v[88:89], v[88:89], v[92:93]
	v_pk_mul_f32 v[92:93], v[94:95], v[160:161] op_sel_hi:[1,0]
	v_cvt_pk_bf16_f32 v88, v88, v89
	v_mul_f32_e32 v94, 0xbfb8aa3b, v92
	v_mul_f32_e32 v95, 0xbfb8aa3b, v93
	v_exp_f32_e32 v94, v94
	v_exp_f32_e32 v95, v95
	v_pk_mul_f32 v[2:3], v[2:3], v[128:129] op_sel:[0,1]
	s_andn2_b64 vcc, exec, s[4:5]
	v_add_f32_e32 v94, 1.0, v94
	v_add_f32_e32 v95, 1.0, v95
	v_rcp_f32_e32 v94, v94
	v_rcp_f32_e32 v95, v95
	s_mov_b32 s20, 0x358637bd
	v_pk_mul_f32 v[92:93], v[92:93], v[94:95]
	s_nop 0
	v_pk_mul_f32 v[90:91], v[90:91], v[92:93]
	s_nop 0
	v_cvt_pk_bf16_f32 v89, v90, v91
	v_mov_b32_e32 v136, v88
	v_mov_b32_e32 v137, v89
	v_mul_f32_e32 v88, 0xbfb8aa3b, v84
	v_mul_f32_e32 v89, 0xbfb8aa3b, v85
	v_exp_f32_e32 v88, v88
	v_exp_f32_e32 v89, v89
	v_add_f32_e32 v88, 1.0, v88
	v_add_f32_e32 v89, 1.0, v89
	v_rcp_f32_e32 v88, v88
	v_rcp_f32_e32 v89, v89
	s_nop 0
	v_pk_mul_f32 v[84:85], v[84:85], v[88:89]
	s_nop 0
	v_pk_mul_f32 v[80:81], v[80:81], v[84:85]
	v_pk_mul_f32 v[84:85], v[86:87], v[160:161] op_sel_hi:[1,0]
	v_cvt_pk_bf16_f32 v80, v80, v81
	v_mul_f32_e32 v86, 0xbfb8aa3b, v84
	v_mul_f32_e32 v87, 0xbfb8aa3b, v85
	v_exp_f32_e32 v86, v86
	v_exp_f32_e32 v87, v87
	v_add_f32_e32 v86, 1.0, v86
	v_add_f32_e32 v87, 1.0, v87
	v_rcp_f32_e32 v86, v86
	v_rcp_f32_e32 v87, v87
	s_nop 0
	v_pk_mul_f32 v[84:85], v[84:85], v[86:87]
	s_nop 0
	v_pk_mul_f32 v[82:83], v[82:83], v[84:85]
	s_nop 0
	v_cvt_pk_bf16_f32 v81, v82, v83
	v_mov_b32_e32 v138, v80
	v_mov_b32_e32 v139, v81
	v_lshl_add_u64 v[140:141], v[96:97], 0, v[142:143]
	s_nop 0
	v_permlane16_swap_b32_e32 v136, v138
	v_permlane16_swap_b32_e32 v137, v139
	global_store_dwordx4 v[140:141], v[136:139], off
	v_mad_u64_u32 v[80:81], s[18:19], v158, s11, v[130:131]
	v_mov_b32_e32 v82, v81
	v_mad_u64_u32 v[82:83], s[18:19], v159, s11, v[82:83]
	v_mov_b32_e32 v81, v82
	v_mul_f32_e32 v82, 0xbfb8aa3b, v76
	v_mul_f32_e32 v83, 0xbfb8aa3b, v77
	v_exp_f32_e32 v82, v82
	v_exp_f32_e32 v83, v83
	v_lshl_add_u64 v[80:81], v[80:81], 0, s[6:7]
	v_lshl_add_u64 v[80:81], v[80:81], 0, s[92:93]
	v_add_f32_e32 v82, 1.0, v82
	v_add_f32_e32 v83, 1.0, v83
	v_rcp_f32_e32 v82, v82
	v_rcp_f32_e32 v83, v83
	v_lshl_add_u64 v[80:81], v[80:81], 0, v[176:177]
	v_pk_mul_f32 v[76:77], v[76:77], v[82:83]
	s_nop 0
	v_pk_mul_f32 v[72:73], v[72:73], v[76:77]
	v_pk_mul_f32 v[76:77], v[78:79], v[160:161] op_sel:[0,1]
	v_cvt_pk_bf16_f32 v72, v72, v73
	v_mul_f32_e32 v78, 0xbfb8aa3b, v76
	v_mul_f32_e32 v79, 0xbfb8aa3b, v77
	v_exp_f32_e32 v78, v78
	v_exp_f32_e32 v79, v79
	v_add_f32_e32 v78, 1.0, v78
	v_add_f32_e32 v79, 1.0, v79
	v_rcp_f32_e32 v78, v78
	v_rcp_f32_e32 v79, v79
	s_nop 0
	v_pk_mul_f32 v[76:77], v[76:77], v[78:79]
	s_nop 0
	v_pk_mul_f32 v[74:75], v[74:75], v[76:77]
	s_nop 0
	v_cvt_pk_bf16_f32 v73, v74, v75
	v_mov_b32_e32 v136, v72
	v_mov_b32_e32 v137, v73
	v_mul_f32_e32 v72, 0xbfb8aa3b, v68
	v_mul_f32_e32 v73, 0xbfb8aa3b, v69
	v_exp_f32_e32 v72, v72
	v_exp_f32_e32 v73, v73
	v_add_f32_e32 v72, 1.0, v72
	v_add_f32_e32 v73, 1.0, v73
	v_rcp_f32_e32 v72, v72
	v_rcp_f32_e32 v73, v73
	s_nop 0
	v_pk_mul_f32 v[68:69], v[68:69], v[72:73]
	s_nop 0
	v_pk_mul_f32 v[64:65], v[64:65], v[68:69]
	v_pk_mul_f32 v[68:69], v[70:71], v[160:161] op_sel:[0,1]
	v_cvt_pk_bf16_f32 v64, v64, v65
	v_mul_f32_e32 v70, 0xbfb8aa3b, v68
	v_mul_f32_e32 v71, 0xbfb8aa3b, v69
	v_exp_f32_e32 v70, v70
	v_exp_f32_e32 v71, v71
	v_add_f32_e32 v70, 1.0, v70
	v_add_f32_e32 v71, 1.0, v71
	v_rcp_f32_e32 v70, v70
	v_rcp_f32_e32 v71, v71
	s_nop 0
	v_pk_mul_f32 v[68:69], v[68:69], v[70:71]
	s_nop 0
	v_pk_mul_f32 v[66:67], v[66:67], v[68:69]
	s_nop 0
	v_cvt_pk_bf16_f32 v65, v66, v67
	v_mov_b32_e32 v138, v64
	v_mov_b32_e32 v139, v65
	v_lshl_add_u64 v[140:141], v[80:81], 0, v[142:143]
	s_nop 0
	v_permlane16_swap_b32_e32 v136, v138
	v_permlane16_swap_b32_e32 v137, v139
	global_store_dwordx4 v[140:141], v[136:139], off
	v_mad_u64_u32 v[64:65], s[18:19], v154, s11, v[130:131]
	v_mov_b32_e32 v66, v65
	v_mad_u64_u32 v[66:67], s[18:19], v155, s11, v[66:67]
	v_mov_b32_e32 v65, v66
	v_mul_f32_e32 v66, 0xbfb8aa3b, v60
	v_mul_f32_e32 v67, 0xbfb8aa3b, v61
	v_exp_f32_e32 v66, v66
	v_exp_f32_e32 v67, v67
	v_lshl_add_u64 v[64:65], v[64:65], 0, s[6:7]
	v_lshl_add_u64 v[64:65], v[64:65], 0, s[92:93]
	v_add_f32_e32 v66, 1.0, v66
	v_add_f32_e32 v67, 1.0, v67
	v_rcp_f32_e32 v66, v66
	v_rcp_f32_e32 v67, v67
	v_lshl_add_u64 v[64:65], v[64:65], 0, v[176:177]
	v_pk_mul_f32 v[60:61], v[60:61], v[66:67]
	s_nop 0
	v_pk_mul_f32 v[56:57], v[56:57], v[60:61]
	v_pk_mul_f32 v[60:61], v[62:63], v[156:157] op_sel_hi:[1,0]
	v_cvt_pk_bf16_f32 v56, v56, v57
	v_mul_f32_e32 v62, 0xbfb8aa3b, v60
	v_mul_f32_e32 v63, 0xbfb8aa3b, v61
	v_exp_f32_e32 v62, v62
	v_exp_f32_e32 v63, v63
	v_add_f32_e32 v62, 1.0, v62
	v_add_f32_e32 v63, 1.0, v63
	v_rcp_f32_e32 v62, v62
	v_rcp_f32_e32 v63, v63
	s_nop 0
	v_pk_mul_f32 v[60:61], v[60:61], v[62:63]
	s_nop 0
	v_pk_mul_f32 v[58:59], v[58:59], v[60:61]
	s_nop 0
	v_cvt_pk_bf16_f32 v57, v58, v59
	v_mov_b32_e32 v136, v56
	v_mov_b32_e32 v137, v57
	v_mul_f32_e32 v56, 0xbfb8aa3b, v52
	v_mul_f32_e32 v57, 0xbfb8aa3b, v53
	v_exp_f32_e32 v56, v56
	v_exp_f32_e32 v57, v57
	v_add_f32_e32 v56, 1.0, v56
	v_add_f32_e32 v57, 1.0, v57
	v_rcp_f32_e32 v56, v56
	v_rcp_f32_e32 v57, v57
	s_nop 0
	v_pk_mul_f32 v[52:53], v[52:53], v[56:57]
	s_nop 0
	v_pk_mul_f32 v[48:49], v[48:49], v[52:53]
	v_pk_mul_f32 v[52:53], v[54:55], v[156:157] op_sel_hi:[1,0]
	v_cvt_pk_bf16_f32 v48, v48, v49
	v_mul_f32_e32 v54, 0xbfb8aa3b, v52
	v_mul_f32_e32 v55, 0xbfb8aa3b, v53
	v_exp_f32_e32 v54, v54
	v_exp_f32_e32 v55, v55
	v_add_f32_e32 v54, 1.0, v54
	v_add_f32_e32 v55, 1.0, v55
	v_rcp_f32_e32 v54, v54
	v_rcp_f32_e32 v55, v55
	s_nop 0
	v_pk_mul_f32 v[52:53], v[52:53], v[54:55]
	s_nop 0
	v_pk_mul_f32 v[50:51], v[50:51], v[52:53]
	s_nop 0
	v_cvt_pk_bf16_f32 v49, v50, v51
	v_mul_f32_e32 v50, 0xbfb8aa3b, v44
	v_mul_f32_e32 v51, 0xbfb8aa3b, v45
	v_exp_f32_e32 v50, v50
	v_exp_f32_e32 v51, v51
	v_mov_b32_e32 v138, v48
	v_mov_b32_e32 v139, v49
	v_lshl_add_u64 v[140:141], v[64:65], 0, v[142:143]
	s_nop 0
	v_permlane16_swap_b32_e32 v136, v138
	v_permlane16_swap_b32_e32 v137, v139
	global_store_dwordx4 v[140:141], v[136:139], off
	v_add_u32_e32 v48, 16, v154
	v_add_f32_e32 v50, 1.0, v50
	v_add_f32_e32 v51, 1.0, v51
	v_rcp_f32_e32 v50, v50
	v_rcp_f32_e32 v51, v51
	v_mad_i64_i32 v[48:49], s[18:19], v48, s11, v[130:131]
	v_lshl_add_u64 v[48:49], v[48:49], 0, s[6:7]
	v_pk_mul_f32 v[44:45], v[44:45], v[50:51]
	v_lshl_add_u64 v[48:49], v[48:49], 0, s[92:93]
	v_pk_mul_f32 v[40:41], v[40:41], v[44:45]
	v_pk_mul_f32 v[44:45], v[46:47], v[156:157] op_sel:[0,1]
	v_lshl_add_u64 v[48:49], v[48:49], 0, v[176:177]
	v_mul_f32_e32 v46, 0xbfb8aa3b, v44
	v_mul_f32_e32 v47, 0xbfb8aa3b, v45
	v_exp_f32_e32 v46, v46
	v_exp_f32_e32 v47, v47
	v_cvt_pk_bf16_f32 v40, v40, v41
	v_add_f32_e32 v46, 1.0, v46
	v_add_f32_e32 v47, 1.0, v47
	v_rcp_f32_e32 v46, v46
	v_rcp_f32_e32 v47, v47
	s_nop 0
	v_pk_mul_f32 v[44:45], v[44:45], v[46:47]
	s_nop 0
	v_pk_mul_f32 v[42:43], v[42:43], v[44:45]
	s_nop 0
	v_cvt_pk_bf16_f32 v41, v42, v43
	v_mov_b32_e32 v136, v40
	v_mov_b32_e32 v137, v41
	v_mul_f32_e32 v40, 0xbfb8aa3b, v36
	v_mul_f32_e32 v41, 0xbfb8aa3b, v37
	v_exp_f32_e32 v40, v40
	v_exp_f32_e32 v41, v41
	v_add_f32_e32 v40, 1.0, v40
	v_add_f32_e32 v41, 1.0, v41
	v_rcp_f32_e32 v40, v40
	v_rcp_f32_e32 v41, v41
	s_nop 0
	v_pk_mul_f32 v[36:37], v[36:37], v[40:41]
	s_nop 0
	v_pk_mul_f32 v[32:33], v[32:33], v[36:37]
	v_pk_mul_f32 v[36:37], v[38:39], v[156:157] op_sel:[0,1]
	v_cvt_pk_bf16_f32 v32, v32, v33
	v_mul_f32_e32 v38, 0xbfb8aa3b, v36
	v_mul_f32_e32 v39, 0xbfb8aa3b, v37
	v_exp_f32_e32 v38, v38
	v_exp_f32_e32 v39, v39
	v_add_f32_e32 v38, 1.0, v38
	v_add_f32_e32 v39, 1.0, v39
	v_rcp_f32_e32 v38, v38
	v_rcp_f32_e32 v39, v39
	s_nop 0
	v_pk_mul_f32 v[36:37], v[36:37], v[38:39]
	s_nop 0
	v_pk_mul_f32 v[34:35], v[34:35], v[36:37]
	s_nop 0
	v_cvt_pk_bf16_f32 v33, v34, v35
	v_mul_f32_e32 v34, 0xbfb8aa3b, v28
	v_mul_f32_e32 v35, 0xbfb8aa3b, v29
	v_exp_f32_e32 v34, v34
	v_exp_f32_e32 v35, v35
	v_mov_b32_e32 v138, v32
	v_mov_b32_e32 v139, v33
	v_lshl_add_u64 v[140:141], v[48:49], 0, v[142:143]
	s_nop 0
	v_permlane16_swap_b32_e32 v136, v138
	v_permlane16_swap_b32_e32 v137, v139
	global_store_dwordx4 v[140:141], v[136:139], off
	v_add_u32_e32 v32, 32, v154
	v_add_f32_e32 v34, 1.0, v34
	v_add_f32_e32 v35, 1.0, v35
	v_rcp_f32_e32 v34, v34
	v_rcp_f32_e32 v35, v35
	v_mad_i64_i32 v[32:33], s[18:19], v32, s11, v[130:131]
	v_lshl_add_u64 v[32:33], v[32:33], 0, s[6:7]
	v_pk_mul_f32 v[28:29], v[28:29], v[34:35]
	v_lshl_add_u64 v[32:33], v[32:33], 0, s[92:93]
	v_pk_mul_f32 v[24:25], v[24:25], v[28:29]
	v_pk_mul_f32 v[28:29], v[30:31], v[128:129] op_sel_hi:[1,0]
	v_lshl_add_u64 v[32:33], v[32:33], 0, v[176:177]
	v_mul_f32_e32 v30, 0xbfb8aa3b, v28
	v_mul_f32_e32 v31, 0xbfb8aa3b, v29
	v_exp_f32_e32 v30, v30
	v_exp_f32_e32 v31, v31
	v_cvt_pk_bf16_f32 v24, v24, v25
	v_add_f32_e32 v30, 1.0, v30
	v_add_f32_e32 v31, 1.0, v31
	v_rcp_f32_e32 v30, v30
	v_rcp_f32_e32 v31, v31
	s_nop 0
	v_pk_mul_f32 v[28:29], v[28:29], v[30:31]
	s_nop 0
	v_pk_mul_f32 v[26:27], v[26:27], v[28:29]
	s_nop 0
	v_cvt_pk_bf16_f32 v25, v26, v27
	v_mov_b32_e32 v136, v24
	v_mov_b32_e32 v137, v25
	v_mul_f32_e32 v24, 0xbfb8aa3b, v20
	v_mul_f32_e32 v25, 0xbfb8aa3b, v21
	v_exp_f32_e32 v24, v24
	v_exp_f32_e32 v25, v25
	v_add_f32_e32 v24, 1.0, v24
	v_add_f32_e32 v25, 1.0, v25
	v_rcp_f32_e32 v24, v24
	v_rcp_f32_e32 v25, v25
	s_nop 0
	v_pk_mul_f32 v[20:21], v[20:21], v[24:25]
	s_nop 0
	v_pk_mul_f32 v[16:17], v[16:17], v[20:21]
	v_pk_mul_f32 v[20:21], v[22:23], v[128:129] op_sel_hi:[1,0]
	v_cvt_pk_bf16_f32 v16, v16, v17
	v_mul_f32_e32 v22, 0xbfb8aa3b, v20
	v_mul_f32_e32 v23, 0xbfb8aa3b, v21
	v_exp_f32_e32 v22, v22
	v_exp_f32_e32 v23, v23
	v_add_f32_e32 v22, 1.0, v22
	v_add_f32_e32 v23, 1.0, v23
	v_rcp_f32_e32 v22, v22
	v_rcp_f32_e32 v23, v23
	s_nop 0
	v_pk_mul_f32 v[20:21], v[20:21], v[22:23]
	s_nop 0
	v_pk_mul_f32 v[18:19], v[18:19], v[20:21]
	s_nop 0
	v_cvt_pk_bf16_f32 v17, v18, v19
	v_mul_f32_e32 v18, 0xbfb8aa3b, v12
	v_mul_f32_e32 v19, 0xbfb8aa3b, v13
	v_exp_f32_e32 v18, v18
	v_exp_f32_e32 v19, v19
	v_mov_b32_e32 v138, v16
	v_mov_b32_e32 v139, v17
	v_lshl_add_u64 v[140:141], v[32:33], 0, v[142:143]
	s_nop 0
	v_permlane16_swap_b32_e32 v136, v138
	v_permlane16_swap_b32_e32 v137, v139
	global_store_dwordx4 v[140:141], v[136:139], off
	v_add_u32_e32 v16, 48, v154
	v_add_f32_e32 v18, 1.0, v18
	v_add_f32_e32 v19, 1.0, v19
	v_rcp_f32_e32 v18, v18
	v_rcp_f32_e32 v19, v19
	v_mad_i64_i32 v[16:17], s[18:19], v16, s11, v[130:131]
	v_lshl_add_u64 v[16:17], v[16:17], 0, s[6:7]
	v_pk_mul_f32 v[12:13], v[12:13], v[18:19]
	v_lshl_add_u64 v[16:17], v[16:17], 0, s[92:93]
	v_pk_mul_f32 v[8:9], v[8:9], v[12:13]
	v_pk_mul_f32 v[12:13], v[14:15], v[128:129] op_sel:[0,1]
	v_lshl_add_u64 v[16:17], v[16:17], 0, v[176:177]
	v_mul_f32_e32 v14, 0xbfb8aa3b, v12
	v_mul_f32_e32 v15, 0xbfb8aa3b, v13
	v_exp_f32_e32 v14, v14
	v_exp_f32_e32 v15, v15
	v_cvt_pk_bf16_f32 v8, v8, v9
	s_mov_b64 s[6:7], -1
	v_add_f32_e32 v14, 1.0, v14
	v_add_f32_e32 v15, 1.0, v15
	v_rcp_f32_e32 v14, v14
	v_rcp_f32_e32 v15, v15
	s_nop 0
	v_pk_mul_f32 v[12:13], v[12:13], v[14:15]
	s_nop 0
	v_pk_mul_f32 v[10:11], v[10:11], v[12:13]
	s_nop 0
	v_cvt_pk_bf16_f32 v9, v10, v11
	v_mov_b32_e32 v136, v8
	v_mov_b32_e32 v137, v9
	v_mul_f32_e32 v8, 0xbfb8aa3b, v4
	v_mul_f32_e32 v9, 0xbfb8aa3b, v5
	v_exp_f32_e32 v8, v8
	v_exp_f32_e32 v9, v9
	v_add_f32_e32 v8, 1.0, v8
	v_add_f32_e32 v9, 1.0, v9
	v_rcp_f32_e32 v8, v8
	v_rcp_f32_e32 v9, v9
	s_nop 0
	v_pk_mul_f32 v[4:5], v[4:5], v[8:9]
	s_nop 0
	v_pk_mul_f32 v[0:1], v[0:1], v[4:5]
	v_pk_mul_f32 v[4:5], v[6:7], v[128:129] op_sel:[0,1]
	v_cvt_pk_bf16_f32 v0, v0, v1
	v_mul_f32_e32 v6, 0xbfb8aa3b, v4
	v_mul_f32_e32 v7, 0xbfb8aa3b, v5
	v_exp_f32_e32 v6, v6
	v_exp_f32_e32 v7, v7
	v_add_f32_e32 v6, 1.0, v6
	v_add_f32_e32 v7, 1.0, v7
	v_rcp_f32_e32 v6, v6
	v_rcp_f32_e32 v7, v7
	s_nop 0
	v_pk_mul_f32 v[4:5], v[4:5], v[6:7]
	s_nop 0
	v_pk_mul_f32 v[2:3], v[2:3], v[4:5]
	s_nop 0
	v_cvt_pk_bf16_f32 v1, v2, v3
	v_mov_b32_e32 v138, v0
	v_mov_b32_e32 v139, v1
	v_lshl_add_u64 v[140:141], v[16:17], 0, v[142:143]
	s_nop 0
	v_permlane16_swap_b32_e32 v136, v138
	v_permlane16_swap_b32_e32 v137, v139
	global_store_dwordx4 v[140:141], v[136:139], off
	s_cbranch_vccnz .LBB0_18
	s_andn2_b64 vcc, exec, s[2:3]
	s_cbranch_vccnz .LBB0_17
	s_barrier
	s_branch .LBB0_17
